# NSA window loop: step-1 K-fragment and tile-index LDS reads issued before the step-0 end barrier (same as selected loop), temps in registers verified free across the whole chunk loop
# baseline (speedup 1.0000x reference)
; DI unsigned cvtpk(float lo, float hi) { f32x2_t v = {lo, hi}; bf16x2_t b = __builtin_convertvector(v, bf16x2_t); return __builtin_bit_cast(unsigned, b); }
; #define MFMA32(a, b, c) __builtin_amdgcn_mfma_f32_32x32x16_bf16((a), (b), (c), 0, 0, 0)
; #define SBAR() __builtin_amdgcn_sched_barrier(0)
; template <int VSTR, int NDVB> DI void pv64(f32x16 (&O)[NDVB], const lds8* vp, const bf16x8 (&P)[4]) {
;   bf16x8 f[2][NDVB];
; #pragma unroll
;   for (int d = 0; d < NDVB; ++d) { const s16x4 lo = trrd(vp + d * 64), hi = trrd(vp + 8 * VSTR + d * 64); f[0][d] = __builtin_shufflevector(lo, hi, 0, 1, 2, 3, 4, 5, 6, 7); }
; #pragma unroll
;   for (int kk = 0; kk < 4; ++kk) {
;     if (kk < 3) {
; #pragma unroll
;       for (int d = 0; d < NDVB; ++d) { const s16x4 lo = trrd(vp + (16 * (kk + 1)) * VSTR + d * 64), hi = trrd(vp + (16 * (kk + 1) + 8) * VSTR + d * 64);
;         f[(kk + 1) & 1][d] = __builtin_shufflevector(lo, hi, 0, 1, 2, 3, 4, 5, 6, 7); }
;     }
;     SBAR();
;     __builtin_amdgcn_s_setprio(1);
; #pragma unroll
;     for (int d = 0; d < NDVB; ++d) O[d] = MFMA32(f[kk & 1][d], P[kk], O[d]);
;     __builtin_amdgcn_s_setprio(0);
;     SBAR();
;   }
; template <int NDVB, bool HAS_NEXT> DI void softmax_def(f32x16& sa0, f32x16& sa1, f32x16& sb0, f32x16& sb1, f32x16 (&O)[NDVB], float& muse, float& l, bool first, bf16x8 (&P)[4], bool check = true) {
;     ...
;   float sum = 0.f;
; #pragma unroll
;   for (int i = 0; i < 16; ++i) { sa0[i] = __builtin_amdgcn_exp2f(sa0[i]); sum += sa0[i]; }
; #pragma unroll
;   for (int i = 0; i < 16; ++i) { sa1[i] = __builtin_amdgcn_exp2f(sa1[i]); sum += sa1[i]; }
;   l += sum;
;   u32x4 w;
;   w.x = cvtpk(sa0[0], sa0[1]); w.y = cvtpk(sa0[2], sa0[3]); w.z = cvtpk(sa0[4], sa0[5]); w.w = cvtpk(sa0[6], sa0[7]); P[0] = __builtin_bit_cast(bf16x8, w);
;   w.x = cvtpk(sa0[8], sa0[9]); w.y = cvtpk(sa0[10], sa0[11]); w.z = cvtpk(sa0[12], sa0[13]); w.w = cvtpk(sa0[14], sa0[15]); P[1] = __builtin_bit_cast(bf16x8, w);
;   w.x = cvtpk(sa1[0], sa1[1]); w.y = cvtpk(sa1[2], sa1[3]); w.z = cvtpk(sa1[4], sa1[5]); w.w = cvtpk(sa1[6], sa1[7]); P[2] = __builtin_bit_cast(bf16x8, w);
;   w.x = cvtpk(sa1[8], sa1[9]); w.y = cvtpk(sa1[10], sa1[11]); w.z = cvtpk(sa1[12], sa1[13]); w.w = cvtpk(sa1[14], sa1[15]); P[3] = __builtin_bit_cast(bf16x8, w);
.LBB0_994:
	v_exp_f32_e32 v141, v124
	v_add_u32_e32 v124, s49, v216
	v_exp_f32_e32 v129, v112
	v_exp_f32_e32 v130, v113
	v_exp_f32_e32 v131, v114
	v_exp_f32_e32 v132, v115
	v_exp_f32_e32 v133, v116
	v_exp_f32_e32 v134, v117
	v_exp_f32_e32 v135, v118
	v_exp_f32_e32 v136, v119
	v_exp_f32_e32 v137, v120
	v_exp_f32_e32 v138, v121
	v_exp_f32_e32 v139, v122
	v_exp_f32_e32 v140, v123
	v_exp_f32_e32 v157, v108
	v_exp_f32_e32 v158, v109
	v_exp_f32_e32 v159, v110
	v_exp_f32_e32 v222, v111
	ds_read_b64_tr_b16 v[108:109], v124 offset:9216
	ds_read_b64_tr_b16 v[110:111], v124 offset:10368
	ds_read_b64_tr_b16 v[114:115], v124 offset:10432
	ds_read_b64_tr_b16 v[112:113], v124 offset:9280
	ds_read_b64_tr_b16 v[116:117], v124 offset:11520
	ds_read_b64_tr_b16 v[118:119], v124 offset:12672
	ds_read_b64_tr_b16 v[122:123], v124 offset:12736
	ds_read_b64_tr_b16 v[120:121], v124 offset:11584
	v_exp_f32_e32 v142, v125
	v_exp_f32_e32 v143, v126
	v_exp_f32_e32 v144, v127
	v_exp_f32_e32 v145, v96
	v_exp_f32_e32 v146, v97
	v_exp_f32_e32 v147, v98
	v_exp_f32_e32 v148, v99
	v_exp_f32_e32 v149, v100
	v_exp_f32_e32 v150, v101
	v_exp_f32_e32 v151, v102
	v_exp_f32_e32 v152, v103
	v_exp_f32_e32 v153, v104
	v_exp_f32_e32 v154, v105
	v_exp_f32_e32 v155, v106
	v_exp_f32_e32 v156, v107
	v_cvt_pk_bf16_f32 v96, v129, v130
	v_cvt_pk_bf16_f32 v97, v131, v132
	v_cvt_pk_bf16_f32 v98, v133, v134
	v_cvt_pk_bf16_f32 v99, v135, v136
	v_cvt_pk_bf16_f32 v100, v137, v138
	v_cvt_pk_bf16_f32 v101, v139, v140
	v_cvt_pk_bf16_f32 v102, v141, v142
	v_cvt_pk_bf16_f32 v103, v143, v144
	v_cvt_pk_bf16_f32 v104, v145, v146
	v_cvt_pk_bf16_f32 v105, v147, v148
	v_cvt_pk_bf16_f32 v106, v149, v150
	v_cvt_pk_bf16_f32 v107, v151, v152
	v_cvt_pk_bf16_f32 v224, v153, v154
	v_cvt_pk_bf16_f32 v225, v155, v156
	v_cvt_pk_bf16_f32 v226, v157, v158
	v_cvt_pk_bf16_f32 v227, v159, v222
	s_setprio 1
	s_waitcnt lgkmcnt(6)
	v_mfma_f32_32x32x16_bf16 v[32:47], v[108:111], v[96:99], v[32:47]
	s_waitcnt lgkmcnt(4)
	v_mfma_f32_32x32x16_bf16 v[48:63], v[112:115], v[96:99], v[48:63]
	s_setprio 0
	ds_read_b64_tr_b16 v[96:97], v124 offset:13824
	ds_read_b64_tr_b16 v[98:99], v124 offset:14976
	ds_read_b64_tr_b16 v[110:111], v124 offset:15040
	ds_read_b64_tr_b16 v[108:109], v124 offset:13888
	s_setprio 1
	s_waitcnt lgkmcnt(6)
	v_mfma_f32_32x32x16_bf16 v[32:47], v[116:119], v[100:103], v[32:47]
	s_waitcnt lgkmcnt(4)
	v_mfma_f32_32x32x16_bf16 v[48:63], v[120:123], v[100:103], v[48:63]
	s_setprio 0
	ds_read_b64_tr_b16 v[112:113], v124 offset:16128
	ds_read_b64_tr_b16 v[114:115], v124 offset:17280
	ds_read_b64_tr_b16 v[230:231], v124 offset:17344
	ds_read_b64_tr_b16 v[228:229], v124 offset:16192
	s_setprio 1
	s_waitcnt lgkmcnt(6)
	v_mfma_f32_32x32x16_bf16 v[32:47], v[96:99], v[104:107], v[32:47]
	s_waitcnt lgkmcnt(4)
	v_mfma_f32_32x32x16_bf16 v[48:63], v[108:111], v[104:107], v[48:63]
	s_setprio 0
	s_setprio 1
	s_waitcnt lgkmcnt(2)
	v_mfma_f32_32x32x16_bf16 v[32:47], v[112:115], v[224:227], v[32:47]
	s_waitcnt lgkmcnt(0)
	v_mfma_f32_32x32x16_bf16 v[48:63], v[228:231], v[224:227], v[48:63]
	s_setprio 0
	s_andn2_b64 vcc, exec, s[42:43]
	s_cbranch_vccnz .LBB0_996
	s_addk_i32 s48, 0xb800
	s_cmp_lg_u32 s6, 0
	s_cselect_b32 s8, s48, 0x9000
	v_add_u32_e32 v234, s8, v215
	s_waitcnt vmcnt(1)
	ds_write_b128 v234, v[176:179]
	s_waitcnt vmcnt(0)
	ds_write_b128 v234, v[180:183] offset:9216
.LBB0_996:
	s_add_i32 s48, s6, 1
	s_cmp_lg_u32 s6, 2
	s_cselect_b32 s48, s48, 0
	s_mul_i32 s48, s48, 0x4800
	v_mov_b32_e32 v235, s0
	v_add_u32_e32 v124, s48, v213
	ds_read_b32 v235, v235 offset:12
	ds_read_b128 v[96:99], v124
	ds_read_b128 v[100:103], v124 offset:32
	ds_read_b128 v[104:107], v124 offset:4608
	ds_read_b128 v[108:111], v124 offset:4640
	ds_read_b128 v[112:115], v124 offset:64
	ds_read_b128 v[116:119], v124 offset:96
	ds_read_b128 v[120:123], v124 offset:4672
	ds_read_b128 v[124:127], v124 offset:4704
	v_add_f32_e32 v234, 0, v129
	v_add_f32_e32 v234, v130, v234
	v_add_f32_e32 v234, v131, v234
	v_add_f32_e32 v234, v132, v234
	v_add_f32_e32 v234, v133, v234
	v_add_f32_e32 v234, v134, v234
	v_add_f32_e32 v234, v135, v234
	v_add_f32_e32 v234, v136, v234
	v_add_f32_e32 v234, v137, v234
	v_add_f32_e32 v234, v138, v234
	v_add_f32_e32 v234, v139, v234
	v_add_f32_e32 v234, v140, v234
	v_add_f32_e32 v234, v141, v234
	v_add_f32_e32 v234, v142, v234
	v_add_f32_e32 v234, v143, v234
	v_add_f32_e32 v234, v144, v234
	v_add_f32_e32 v234, v145, v234
	v_add_f32_e32 v234, v146, v234
	v_add_f32_e32 v234, v147, v234
	v_add_f32_e32 v234, v148, v234
	v_add_f32_e32 v234, v149, v234
	v_add_f32_e32 v234, v150, v234
	v_add_f32_e32 v234, v151, v234
	v_add_f32_e32 v234, v152, v234
	v_add_f32_e32 v234, v153, v234
	v_add_f32_e32 v234, v154, v234
	v_add_f32_e32 v234, v155, v234
	v_add_f32_e32 v234, v156, v234
	v_add_f32_e32 v234, v157, v234
	v_add_f32_e32 v234, v158, v234
	v_add_f32_e32 v234, v159, v234
	v_add_f32_e32 v234, v222, v234
	s_add_i32 s10, s46, -2
	v_add_f32_e32 v222, v128, v234
	s_mov_b64 s[8:9], -1
	s_cmp_ge_u32 s10, s3
	s_mov_b64 s[10:11], -1
	s_waitcnt lgkmcnt(0)
	s_barrier
	s_cbranch_scc1 .LBB0_980
	s_cmp_lt_u32 s46, s3
	s_cselect_b64 s[42:43], -1, 0
	s_add_i32 s8, s6, 1
	s_cmp_lg_u32 s6, 2
	s_cselect_b32 s6, s8, 0
	s_mul_i32 s48, s6, 0x4800
	s_add_i32 s49, s48, 0
	s_cmp_ge_u32 s46, s3
	s_cbranch_scc1 .Lwin1_noload
	s_waitcnt lgkmcnt(8)
	v_readfirstlane_b32 s8, v235
	s_nop 1
	v_lshl_add_u32 v128, s8, 6, v212
	v_ashrrev_i32_e32 v129, 31, v128
	v_lshlrev_b64 v[128:129], 9, v[128:129]
	v_lshl_add_u64 v[130:131], v[194:195], 0, v[128:129]
	v_lshl_add_u64 v[128:129], v[196:197], 0, v[128:129]
	global_load_dwordx4 v[176:179], v[130:131], off offset:256
	global_load_dwordx4 v[180:183], v[128:129], off offset:256
